# NSA selection rank-count loops: LDS read software-pipelined one iteration ahead
# baseline (speedup 1.0000x reference)
; DI float ex2(float x) { return __builtin_amdgcn_exp2f(x); }
; DI void nsa_unit(const Params& P, int l, LAS char* lds, int b, int qt, int tid, int wave, int lane) {
;     ...
;     for (int st = 0; st < nst; ++st) {
;         const f32x16 s = qk_rows<0, 4>(kcL, 32 * st, qf, r, h);
;         float p[16];
; #pragma unroll
;         for (int i = 0; i < 16; ++i) { const int n = 32 * st + (i & 3) + 8 * (i >> 2) + 4 * h; const bool ok = (16 * n + 31 <= qpos); p[i] = ok ? ex2(s[i] * c - m) * linv : 0.f; }
;         float pc[4];
; #pragma unroll
;         for (int g = 0; g < 4; ++g) pc[g] = shx32(p[4 * g + 3], lane);
; #pragma unroll
;         for (int g = 0; g < 4; ++g) {
;             const float a = 2.0f * ((p[4 * g] + p[4 * g + 1]) + p[4 * g + 2]) + p[4 * g + 3];
;             const float pred = (h == 1) ? pc[g] : (g > 0 ? pc[g > 0 ? g - 1 : 0] : prevpc3);
;             impH[(hd * 64 + 32 * qh + r) * 64 + 8 * st + 2 * g + h] = a + pred;
;         }
;         prevpc3 = pc[3];
;         bf16x8 pf[2]; pack_p(p, pf);
;         pv_rows(o, vcL, 32 * st, pf, lane);
;     }
.LBB0_515:
	v_add_u32_e32 v36, 0, v52
	ds_read_b128 v[32:35], v36
	ds_read_b128 v[60:63], v36 offset:32
	ds_read_b128 v[66:69], v36 offset:64
	ds_read_b128 v[70:73], v36 offset:96
	s_setprio 1
	s_waitcnt lgkmcnt(3)
	v_mfma_f32_32x32x16_bf16 v[32:47], v[32:35], v[96:99], 0
	s_waitcnt lgkmcnt(2)
	v_mfma_f32_32x32x16_bf16 v[32:47], v[60:63], v[100:103], v[32:47]
	s_waitcnt lgkmcnt(1)
	v_mfma_f32_32x32x16_bf16 v[32:47], v[66:69], v[104:107], v[32:47]
	s_waitcnt lgkmcnt(0)
	v_mfma_f32_32x32x16_bf16 v[32:47], v[70:73], v[108:111], v[32:47]
	s_setprio 0
	s_nop 10
	v_sub_f32_e32 v32, v32, v54
	v_sub_f32_e32 v33, v33, v54
	v_exp_f32_e32 v32, v32
	v_exp_f32_e32 v33, v33
	v_or_b32_e32 v59, 47, v53
	v_cmp_le_i32_e32 vcc, v59, v51
	v_or_b32_e32 v60, 31, v53
	v_pk_mul_f32 v[32:33], v[48:49], v[32:33]
	s_nop 0
	v_cndmask_b32_e32 v59, 0, v33, vcc
	v_sub_f32_e32 v33, v34, v54
	v_exp_f32_e32 v33, v33
	v_cmp_le_i32_e32 vcc, v60, v160
	v_mul_f32_e32 v33, v48, v33
	s_nop 0
	v_cndmask_b32_e32 v60, 0, v32, vcc
	v_add_u32_e32 v32, 63, v53
	v_cmp_le_i32_e32 vcc, v32, v160
	v_add_u32_e32 v32, 0x4f, v53
	v_add_f32_e32 v66, v60, v59
	v_cndmask_b32_e32 v34, 0, v33, vcc
	v_sub_f32_e32 v33, v35, v54
	v_exp_f32_e32 v33, v33
	v_cmp_le_i32_e32 vcc, v32, v160
	v_sub_f32_e32 v32, v36, v54
	v_exp_f32_e32 v32, v32
	v_mul_f32_e32 v33, v48, v33
	v_cndmask_b32_e32 v35, 0, v33, vcc
	v_sub_f32_e32 v33, v37, v54
	v_exp_f32_e32 v33, v33
	v_or_b32_e32 v36, 0xaf, v53
	v_cmp_le_i32_e32 vcc, v36, v51
	v_or_b32_e32 v37, 0x9f, v53
	v_pk_mul_f32 v[32:33], v[48:49], v[32:33]
	v_add_f32_e32 v66, v34, v66
	v_cndmask_b32_e32 v36, 0, v33, vcc
	v_sub_f32_e32 v33, v38, v54
	v_exp_f32_e32 v33, v33
	v_cmp_le_i32_e32 vcc, v37, v160
	v_fma_f32 v66, 2.0, v66, v35
	v_mul_f32_e32 v33, v48, v33
	v_cndmask_b32_e32 v37, 0, v32, vcc
	v_add_u32_e32 v32, 0xbf, v53
	v_cmp_le_i32_e32 vcc, v32, v160
	v_add_u32_e32 v32, 0xcf, v53
	s_nop 0
	v_cndmask_b32_e32 v38, 0, v33, vcc
	v_sub_f32_e32 v33, v39, v54
	v_exp_f32_e32 v33, v33
	v_cmp_le_i32_e32 vcc, v32, v160
	v_sub_f32_e32 v32, v40, v54
	v_exp_f32_e32 v32, v32
	v_mul_f32_e32 v33, v48, v33
	v_cndmask_b32_e32 v39, 0, v33, vcc
	v_sub_f32_e32 v33, v41, v54
	v_exp_f32_e32 v33, v33
	v_or_b32_e32 v40, 0x12f, v53
	v_cmp_le_i32_e32 vcc, v40, v51
	v_or_b32_e32 v41, 0x11f, v53
	v_pk_mul_f32 v[32:33], v[48:49], v[32:33]
	v_mov_b32_e32 v61, v39
	v_cndmask_b32_e32 v40, 0, v33, vcc
	v_sub_f32_e32 v33, v42, v54
	v_exp_f32_e32 v33, v33
	v_cmp_le_i32_e32 vcc, v41, v160
	v_mul_f32_e32 v33, v48, v33
	s_nop 0
	v_cndmask_b32_e32 v41, 0, v32, vcc
	v_add_u32_e32 v32, 0x13f, v53
	v_cmp_le_i32_e32 vcc, v32, v160
	v_add_u32_e32 v32, 0x14f, v53
	s_nop 0
	v_cndmask_b32_e32 v42, 0, v33, vcc
	v_sub_f32_e32 v33, v43, v54
	v_exp_f32_e32 v33, v33
	v_cmp_le_i32_e32 vcc, v32, v160
	v_sub_f32_e32 v32, v44, v54
	v_exp_f32_e32 v32, v32
	v_mul_f32_e32 v33, v48, v33
	v_cndmask_b32_e32 v43, 0, v33, vcc
	v_sub_f32_e32 v33, v45, v54
	v_exp_f32_e32 v33, v33
	v_or_b32_e32 v44, 0x1af, v53
	v_cmp_le_i32_e32 vcc, v44, v51
	v_or_b32_e32 v45, 0x19f, v53
	v_pk_mul_f32 v[32:33], v[48:49], v[32:33]
	v_mov_b32_e32 v62, v43
	v_cndmask_b32_e32 v44, 0, v33, vcc
	v_sub_f32_e32 v33, v46, v54
	v_exp_f32_e32 v33, v33
	v_cmp_le_i32_e32 vcc, v45, v160
	v_mul_f32_e32 v33, v48, v33
	s_nop 0
	v_cndmask_b32_e32 v45, 0, v32, vcc
	v_add_u32_e32 v32, 0x1bf, v53
	v_cmp_le_i32_e32 vcc, v32, v160
	v_add_u32_e32 v32, 0x1cf, v53
	s_nop 0
	v_cndmask_b32_e32 v46, 0, v33, vcc
	v_sub_f32_e32 v33, v47, v54
	v_exp_f32_e32 v33, v33
	v_cmp_le_i32_e32 vcc, v32, v160
	v_mov_b32_e32 v32, v35
	v_mul_f32_e32 v33, v48, v33
	v_cndmask_b32_e32 v47, 0, v33, vcc
	v_mov_b32_e32 v33, v35
	s_nop 1
	v_permlane32_swap_b32_e32 v32, v33
	v_cndmask_b32_e64 v32, v32, v33, s[36:37]
	v_mov_b32_e32 v33, v39
	s_nop 1
	v_permlane32_swap_b32_e32 v33, v61
	v_cndmask_b32_e64 v33, v33, v61, s[36:37]
	v_mov_b32_e32 v61, v43
	s_nop 1
	v_permlane32_swap_b32_e32 v61, v62
	v_cndmask_b32_e64 v61, v61, v62, s[36:37]
	v_mov_b32_e32 v62, v47
	v_mov_b32_e32 v63, v47
	s_nop 1
	v_permlane32_swap_b32_e32 v62, v63
	v_cndmask_b32_e64 v62, v62, v63, s[36:37]
	v_add_u32_e32 v63, 0, v57
	v_cndmask_b32_e64 v58, v32, v58, s[36:37]
	v_add_u32_e32 v65, 0x12000, v63
	v_add_f32_e32 v58, v58, v66
	ds_write_b32 v65, v58
	v_add_f32_e32 v58, v37, v36
	v_add_f32_e32 v58, v38, v58
	v_fma_f32 v58, 2.0, v58, v39
	v_cndmask_b32_e64 v32, v33, v32, s[36:37]
	v_add_f32_e32 v32, v32, v58
	v_add_u32_e32 v58, 0x12008, v63
	ds_write_b32 v58, v32
	v_add_f32_e32 v32, v41, v40
	v_add_f32_e32 v32, v42, v32
	v_fma_f32 v32, 2.0, v32, v43
	v_cndmask_b32_e64 v33, v61, v33, s[36:37]
	v_add_f32_e32 v32, v33, v32
	v_add_u32_e32 v33, 0x12010, v63
	ds_write_b32 v33, v32
	v_add_f32_e32 v32, v45, v44
	v_add_f32_e32 v32, v46, v32
	v_fma_f32 v32, 2.0, v32, v47
	v_cndmask_b32_e64 v33, v62, v61, s[36:37]
	v_add_f32_e32 v32, v32, v33
	v_add_u32_e32 v33, 0x12018, v63
	ds_write_b32 v33, v32
	v_add_u32_e32 v63, 0, v55
	v_cvt_pk_bf16_f32 v32, v60, v59
	v_cvt_pk_bf16_f32 v33, v34, v35
	v_cvt_pk_bf16_f32 v34, v37, v36
	v_cvt_pk_bf16_f32 v35, v38, v39
	v_cvt_pk_bf16_f32 v36, v41, v40
	v_cvt_pk_bf16_f32 v37, v42, v43
	v_cvt_pk_bf16_f32 v38, v45, v44
	v_cvt_pk_bf16_f32 v39, v46, v47
	ds_read_b64_tr_b16 v[40:41], v63 offset:36864
	ds_read_b64_tr_b16 v[42:43], v63 offset:38016
	ds_read_b64_tr_b16 v[44:45], v63 offset:39168
	ds_read_b64_tr_b16 v[46:47], v63 offset:40320
	ds_read_b64_tr_b16 v[58:59], v63 offset:36928
	ds_read_b64_tr_b16 v[60:61], v63 offset:38080
	ds_read_b64_tr_b16 v[66:67], v63 offset:39232
	ds_read_b64_tr_b16 v[68:69], v63 offset:40384
	s_setprio 1
	s_waitcnt lgkmcnt(6)
	v_mfma_f32_32x32x16_bf16 v[0:15], v[40:43], v[32:35], v[0:15]
	s_waitcnt lgkmcnt(2)
	v_mfma_f32_32x32x16_bf16 v[16:31], v[58:61], v[32:35], v[16:31]
	v_mfma_f32_32x32x16_bf16 v[0:15], v[44:47], v[36:39], v[0:15]
	s_waitcnt lgkmcnt(0)
	v_mfma_f32_32x32x16_bf16 v[16:31], v[66:69], v[36:39], v[16:31]
	s_setprio 0
	s_add_i32 s0, s0, -1
	v_add_u32_e32 v55, 0x1200, v55
	v_add_u32_e32 v52, 0x1200, v52
	v_add_u32_e32 v57, 32, v57
	v_add_u32_e32 v53, 0x200, v53
	s_cmp_eq_u32 s0, 0
	v_mov_b32_e32 v58, v62
	s_cbranch_scc0 .LBB0_515
; #define LAS __attribute__((address_space(3)))
; DI void nsa_unit(const Params& P, int l, LAS char* lds, int b, int qt, int tid, int wave, int lane) {
;     ...
;     Stage2 stS; flash_prefetch(stS, hb + (size_t)b * SEQ * NIN + C_KS, hb + (size_t)b * SEQ * NIN + C_VS, NIN, 0, qt, tid);
;     {
;         LAS float* impS = (LAS float*)lds;
;         LAS unsigned long long* selm = (LAS unsigned long long*)(lds + NSA_SELM);
;         const int q = tid >> 3, s8 = tid & 7;
;         if (qt <= 15) { if (s8 == 0) selm[q] = (2ull << qt) - 1ull; }
;         else {
; #pragma unroll
;             for (int e = 0; e < 8; ++e) { const int J = 8 * s8 + e; impS[q * 65 + J] = ((impH[(0 * 64 + q) * 64 + J] + impH[(1 * 64 + q) * 64 + J]) + impH[(2 * 64 + q) * 64 + J]) + impH[(3 * 64 + q) * 64 + J]; }
;             __syncthreads();
;             unsigned bits = 0;
; #pragma unroll
;             for (int e = 0; e < 8; ++e) {
;                 const int J = 8 * s8 + e;
;                 if (J >= 1 && J <= qt - 2) {
;                     const float v = impS[q * 65 + J]; int cnt = 0;
;                     for (int J2 = 1; J2 <= qt - 2; ++J2) { const float v2 = impS[q * 65 + J2]; cnt += (v2 > v || (v2 == v && J2 < J)) ? 1 : 0; }
;                     if (cnt < 13) bits |= 1u << e;
	s_mul_i32 s48, s48, 0x1800000
	s_add_u32 s61, s28, s48
	s_addc_u32 s27, s29, 0
	s_add_u32 s52, s61, 0x1500
	s_addc_u32 s53, s27, 0
	s_add_u32 s54, s61, 0x1580
	s_addc_u32 s55, s27, 0
	v_ashrrev_i32_e32 v187, 3, v56
	s_cmp_eq_u32 s60, 63
	v_mad_i64_i32 v[32:33], s[0:1], v187, s18, 0
	v_lshlrev_b32_e32 v34, 3, v86
	v_and_b32_e32 v212, 56, v34
	s_cselect_b32 s0, 0, 64
	v_or_b32_e32 v32, v32, v212
	v_add_u32_e32 v34, s0, v187
	v_mad_i64_i32 v[34:35], s[0:1], v34, s18, 0
	v_lshlrev_b64 v[32:33], 1, v[32:33]
	v_or_b32_e32 v34, v34, v212
	v_lshl_add_u64 v[36:37], s[52:53], 0, v[32:33]
	v_lshl_add_u64 v[32:33], s[54:55], 0, v[32:33]
	s_barrier
	global_load_dwordx4 v[112:115], v[36:37], off
	global_load_dwordx4 v[116:119], v[32:33], off
	v_lshlrev_b64 v[32:33], 1, v[34:35]
	v_lshl_add_u64 v[34:35], s[52:53], 0, v[32:33]
	v_lshl_add_u64 v[32:33], s[54:55], 0, v[32:33]
	global_load_dwordx4 v[120:123], v[34:35], off
	global_load_dwordx4 v[124:127], v[32:33], off
	v_and_b32_e32 v36, 7, v86
	s_cmp_gt_u32 s58, 15
	v_lshlrev_b32_e32 v162, 3, v36
	v_cmp_eq_u32_e64 s[0:1], 0, v36
	s_cbranch_scc0 .LBB0_522
	v_lshlrev_b32_e32 v32, 8, v187
	s_add_i32 s10, 0, 0x12000
	v_lshlrev_b32_e32 v33, 5, v36
	v_add3_u32 v32, s10, v32, v33
	ds_read_b32 v34, v32
	ds_read_b32 v35, v32 offset:16384
	s_movk_i32 s11, 0x104
	v_mul_lo_u32 v37, v187, s11
	v_add3_u32 v38, 0, v37, v33
	s_sub_i32 s11, 61, s60
	s_waitcnt lgkmcnt(0)
	v_add_f32_e32 v34, v34, v35
	ds_read_b32 v35, v32 offset:32768
	v_cmp_ne_u32_e32 vcc, 0, v36
	v_cmp_ge_u32_e64 s[38:39], s11, v162
	s_sub_i32 s10, 62, s60
	v_mov_b32_e32 v39, 0
	s_waitcnt lgkmcnt(0)
	v_add_f32_e32 v34, v34, v35
	ds_read_b32 v35, v32 offset:49152
	s_and_b64 s[24:25], vcc, s[38:39]
	s_waitcnt lgkmcnt(0)
	v_add_f32_e32 v34, v34, v35
	ds_write_b32 v38, v34
	ds_read_b32 v33, v32 offset:4
	ds_read_b32 v34, v32 offset:16388
	s_waitcnt lgkmcnt(0)
	v_add_f32_e32 v33, v33, v34
	ds_read_b32 v34, v32 offset:32772
	s_waitcnt lgkmcnt(0)
	v_add_f32_e32 v33, v33, v34
	ds_read_b32 v34, v32 offset:49156
	s_waitcnt lgkmcnt(0)
	v_add_f32_e32 v33, v33, v34
	ds_write_b32 v38, v33 offset:4
	ds_read_b32 v33, v32 offset:8
	ds_read_b32 v34, v32 offset:16392
	s_waitcnt lgkmcnt(0)
	v_add_f32_e32 v33, v33, v34
	ds_read_b32 v34, v32 offset:32776
	s_waitcnt lgkmcnt(0)
	v_add_f32_e32 v33, v33, v34
	ds_read_b32 v34, v32 offset:49160
	s_waitcnt lgkmcnt(0)
	v_add_f32_e32 v33, v33, v34
	ds_write_b32 v38, v33 offset:8
	ds_read_b32 v33, v32 offset:12
	ds_read_b32 v34, v32 offset:16396
	s_waitcnt lgkmcnt(0)
	v_add_f32_e32 v33, v33, v34
	ds_read_b32 v34, v32 offset:32780
	s_waitcnt lgkmcnt(0)
	v_add_f32_e32 v33, v33, v34
	ds_read_b32 v34, v32 offset:49164
	s_waitcnt lgkmcnt(0)
	v_add_f32_e32 v33, v33, v34
	ds_write_b32 v38, v33 offset:12
	ds_read_b32 v33, v32 offset:16
	ds_read_b32 v34, v32 offset:16400
	s_waitcnt lgkmcnt(0)
	v_add_f32_e32 v33, v33, v34
	ds_read_b32 v34, v32 offset:32784
	s_waitcnt lgkmcnt(0)
	v_add_f32_e32 v33, v33, v34
	ds_read_b32 v34, v32 offset:49168
	s_waitcnt lgkmcnt(0)
	v_add_f32_e32 v33, v33, v34
	ds_write_b32 v38, v33 offset:16
	ds_read_b32 v33, v32 offset:20
	ds_read_b32 v34, v32 offset:16404
	s_waitcnt lgkmcnt(0)
	v_add_f32_e32 v33, v33, v34
	ds_read_b32 v34, v32 offset:32788
	s_waitcnt lgkmcnt(0)
	v_add_f32_e32 v33, v33, v34
	ds_read_b32 v34, v32 offset:49172
	s_waitcnt lgkmcnt(0)
	v_add_f32_e32 v33, v33, v34
	ds_write_b32 v38, v33 offset:20
	ds_read_b32 v33, v32 offset:24
	ds_read_b32 v34, v32 offset:16408
	s_waitcnt lgkmcnt(0)
	v_add_f32_e32 v33, v33, v34
	ds_read_b32 v34, v32 offset:32792
	s_waitcnt lgkmcnt(0)
	v_add_f32_e32 v33, v33, v34
	ds_read_b32 v34, v32 offset:49176
	s_waitcnt lgkmcnt(0)
	v_add_f32_e32 v33, v33, v34
	ds_write_b32 v38, v33 offset:24
	ds_read_b32 v33, v32 offset:28
	ds_read_b32 v34, v32 offset:16412
	s_waitcnt lgkmcnt(0)
	v_add_f32_e32 v33, v33, v34
	ds_read_b32 v34, v32 offset:32796
	ds_read_b32 v32, v32 offset:49180
	s_waitcnt lgkmcnt(1)
	v_add_f32_e32 v33, v33, v34
	s_waitcnt lgkmcnt(0)
	v_add_f32_e32 v32, v33, v32
	ds_write_b32 v38, v32 offset:28
	s_waitcnt lgkmcnt(0)
	s_barrier
	s_and_saveexec_b64 s[34:35], s[24:25]
	s_cbranch_execz .LBB0_527
	ds_read_b32 v32, v38
	s_cmp_lt_u32 s11, 2
	s_cbranch_scc1 .LBB0_523
	s_and_b32 s24, s11, -2
	s_waitcnt lgkmcnt(0)
	v_mov_b32_e32 v33, v32
	v_mov_b32_e32 v35, v162
	v_add3_u32 v39, 0, 4, v37
	v_mov_b32_e32 v34, 0
	s_mov_b32 s25, 2
	s_mov_b32 s26, 1
	s_mov_b32 s56, s24
	v_mov_b32_e32 v40, 0
	ds_read2_b32 v[250:251], v39 offset1:1
.LBB0_520:
	s_waitcnt lgkmcnt(0)
	v_mov_b32_e32 v42, v250
	v_mov_b32_e32 v43, v251
	ds_read2_b32 v[250:251], v39 offset0:2 offset1:3
	v_cmp_lt_u32_e32 vcc, s26, v162
	v_cmp_lt_u32_e64 s[38:39], s25, v35
	s_add_i32 s26, s26, 2
	s_add_i32 s25, s25, 2
	v_cmp_eq_f32_e64 s[44:45], v42, v32
	v_cmp_eq_f32_e64 s[48:49], v43, v33
	v_cmp_gt_f32_e64 s[40:41], v43, v33
	v_cmp_gt_f32_e64 s[42:43], v42, v32
	s_and_b64 s[38:39], s[48:49], s[38:39]
	s_and_b64 s[44:45], s[44:45], vcc
	s_add_i32 s56, s56, -2
	s_or_b64 vcc, s[42:43], s[44:45]
	s_or_b64 s[38:39], s[40:41], s[38:39]
	v_add_u32_e32 v39, 8, v39
	v_addc_co_u32_e64 v40, s[38:39], 0, v40, s[38:39]
	s_cmp_lg_u32 s56, 0
	v_addc_co_u32_e32 v34, vcc, 0, v34, vcc
	s_cbranch_scc1 .LBB0_520
	s_or_b32 s25, s11, 1
	s_cmp_lg_u32 s11, s24
	v_add_u32_e32 v33, v34, v40
	s_cselect_b64 s[38:39], -1, 0
	s_and_b64 vcc, exec, s[38:39]
	s_cbranch_vccnz .LBB0_524
	s_branch .LBB0_526

; DI void nsa_unit(const Params& P, int l, LAS char* lds, int b, int qt, int tid, int wave, int lane) {
;     ...
;             for (int e = 0; e < 8; ++e) {
;                 const int J = 8 * s8 + e;
;                 if (J >= 1 && J <= qt - 2) {
;                     const float v = impS[q * 65 + J]; int cnt = 0;
;                     for (int J2 = 1; J2 <= qt - 2; ++J2) { const float v2 = impS[q * 65 + J2]; cnt += (v2 > v || (v2 == v && J2 < J)) ? 1 : 0; }
;                     if (cnt < 13) bits |= 1u << e;
.LBB0_527:
	s_or_b64 exec, exec, s[34:35]
	v_cmp_gt_u32_e32 vcc, s11, v162
	s_and_saveexec_b64 s[34:35], vcc
	s_cbranch_execz .LBB0_536
	s_waitcnt lgkmcnt(0)
	ds_read_b32 v32, v38 offset:4
	s_cmp_lt_u32 s11, 2
	s_cbranch_scc1 .LBB0_532
	s_and_b32 s24, s11, -2
	s_waitcnt lgkmcnt(0)
	v_mov_b32_e32 v33, v32
	v_mov_b32_e32 v35, v162
	v_add3_u32 v40, 0, 4, v37
	v_mov_b32_e32 v34, 0
	s_mov_b32 s25, 2
	s_mov_b32 s26, 1
	s_mov_b32 s56, s24
	v_mov_b32_e32 v41, 0
	ds_read2_b32 v[250:251], v40 offset1:1
.LBB0_530:
	s_waitcnt lgkmcnt(0)
	v_mov_b32_e32 v42, v250
	v_mov_b32_e32 v43, v251
	ds_read2_b32 v[250:251], v40 offset0:2 offset1:3
	v_cmp_le_u32_e32 vcc, s26, v162
	v_cmp_le_u32_e64 s[38:39], s25, v35
	s_add_i32 s26, s26, 2
	s_add_i32 s25, s25, 2
	v_cmp_eq_f32_e64 s[44:45], v42, v32
	v_cmp_eq_f32_e64 s[48:49], v43, v33
	v_cmp_gt_f32_e64 s[40:41], v43, v33
	v_cmp_gt_f32_e64 s[42:43], v42, v32
	s_and_b64 s[38:39], s[48:49], s[38:39]
	s_and_b64 s[44:45], s[44:45], vcc
	s_add_i32 s56, s56, -2
	s_or_b64 vcc, s[42:43], s[44:45]
	s_or_b64 s[38:39], s[40:41], s[38:39]
	v_add_u32_e32 v40, 8, v40
	v_addc_co_u32_e64 v41, s[38:39], 0, v41, s[38:39]
	s_cmp_lg_u32 s56, 0
	v_addc_co_u32_e32 v34, vcc, 0, v34, vcc
	s_cbranch_scc1 .LBB0_530
	s_or_b32 s25, s11, 1
	s_cmp_lg_u32 s11, s24
	v_add_u32_e32 v33, v34, v41
	s_cselect_b64 s[38:39], -1, 0
	s_and_b64 vcc, exec, s[38:39]
	s_cbranch_vccnz .LBB0_533
	s_branch .LBB0_535

; DI void nsa_unit(const Params& P, int l, LAS char* lds, int b, int qt, int tid, int wave, int lane) {
;     ...
;             for (int e = 0; e < 8; ++e) {
;                 const int J = 8 * s8 + e;
;                 if (J >= 1 && J <= qt - 2) {
;                     const float v = impS[q * 65 + J]; int cnt = 0;
;                     for (int J2 = 1; J2 <= qt - 2; ++J2) { const float v2 = impS[q * 65 + J2]; cnt += (v2 > v || (v2 == v && J2 < J)) ? 1 : 0; }
;                     if (cnt < 13) bits |= 1u << e;
.LBB0_536:
	s_or_b64 exec, exec, s[34:35]
	s_waitcnt lgkmcnt(0)
	v_or_b32_e32 v32, 2, v162
	v_cmp_ge_u32_e32 vcc, s11, v32
	v_add3_u32 v40, 0, 4, v37
	s_and_saveexec_b64 s[34:35], vcc
	s_cbranch_execz .LBB0_543
	ds_read_b32 v34, v38 offset:8
	s_and_b32 s24, s11, -2
	v_mov_b32_e32 v33, v32
	v_add3_u32 v42, 0, 4, v37
	v_mov_b32_e32 v41, 0
	s_waitcnt lgkmcnt(0)
	v_mov_b32_e32 v35, v34
	s_mov_b32 s25, 2
	s_mov_b32 s26, 1
	s_mov_b32 s56, s24
	v_mov_b32_e32 v43, 0
	ds_read2_b32 v[250:251], v42 offset1:1
.LBB0_538:
	s_waitcnt lgkmcnt(0)
	v_mov_b32_e32 v44, v250
	v_mov_b32_e32 v45, v251
	ds_read2_b32 v[250:251], v42 offset0:2 offset1:3
	v_cmp_lt_u32_e32 vcc, s26, v32
	v_cmp_lt_u32_e64 s[38:39], s25, v33
	s_add_i32 s26, s26, 2
	s_add_i32 s25, s25, 2
	v_cmp_eq_f32_e64 s[44:45], v44, v34
	v_cmp_eq_f32_e64 s[48:49], v45, v35
	v_cmp_gt_f32_e64 s[40:41], v45, v35
	v_cmp_gt_f32_e64 s[42:43], v44, v34
	s_and_b64 s[38:39], s[48:49], s[38:39]
	s_and_b64 s[44:45], s[44:45], vcc
	s_add_i32 s56, s56, -2
	s_or_b64 vcc, s[42:43], s[44:45]
	s_or_b64 s[38:39], s[40:41], s[38:39]
	v_add_u32_e32 v42, 8, v42
	v_addc_co_u32_e64 v43, s[38:39], 0, v43, s[38:39]
	s_cmp_lg_u32 s56, 0
	v_addc_co_u32_e32 v41, vcc, 0, v41, vcc
	s_cbranch_scc1 .LBB0_538
	s_cmp_eq_u32 s11, s24
	v_add_u32_e32 v33, v41, v43
	s_cbranch_scc1 .LBB0_542
	s_or_b32 s24, s11, 1
	s_lshl_b32 s25, s24, 2
	s_add_i32 s25, s25, 0
	v_add_u32_e32 v35, s25, v37

; DI void nsa_unit(const Params& P, int l, LAS char* lds, int b, int qt, int tid, int wave, int lane) {
;     ...
;             for (int e = 0; e < 8; ++e) {
;                 const int J = 8 * s8 + e;
;                 if (J >= 1 && J <= qt - 2) {
;                     const float v = impS[q * 65 + J]; int cnt = 0;
;                     for (int J2 = 1; J2 <= qt - 2; ++J2) { const float v2 = impS[q * 65 + J2]; cnt += (v2 > v || (v2 == v && J2 < J)) ? 1 : 0; }
;                     if (cnt < 13) bits |= 1u << e;
.LBB0_543:
	s_or_b64 exec, exec, s[34:35]
	v_or_b32_e32 v32, 3, v162
	v_cmp_ge_u32_e32 vcc, s11, v32
	s_and_saveexec_b64 s[34:35], vcc
	s_cbranch_execz .LBB0_550
	ds_read_b32 v34, v38 offset:12
	s_and_b32 s24, s11, -2
	v_mov_b32_e32 v33, v32
	v_add3_u32 v42, 0, 4, v37
	v_mov_b32_e32 v41, 0
	s_waitcnt lgkmcnt(0)
	v_mov_b32_e32 v35, v34
	s_mov_b32 s25, 2
	s_mov_b32 s26, 1
	s_mov_b32 s56, s24
	v_mov_b32_e32 v43, 0
	ds_read2_b32 v[250:251], v42 offset1:1

; DI void nsa_unit(const Params& P, int l, LAS char* lds, int b, int qt, int tid, int wave, int lane) {
;     ...
;             for (int e = 0; e < 8; ++e) {
;                 const int J = 8 * s8 + e;
;                 if (J >= 1 && J <= qt - 2) {
;                     const float v = impS[q * 65 + J]; int cnt = 0;
;                     for (int J2 = 1; J2 <= qt - 2; ++J2) { const float v2 = impS[q * 65 + J2]; cnt += (v2 > v || (v2 == v && J2 < J)) ? 1 : 0; }
;                     if (cnt < 13) bits |= 1u << e;
.LBB0_550:
	s_or_b64 exec, exec, s[34:35]
	v_or_b32_e32 v32, 4, v162
	v_cmp_ge_u32_e32 vcc, s11, v32
	s_and_saveexec_b64 s[34:35], vcc
	s_cbranch_execz .LBB0_557
	ds_read_b32 v34, v38 offset:16
	s_and_b32 s24, s11, -2
	v_mov_b32_e32 v33, v32
	v_add3_u32 v42, 0, 4, v37
	v_mov_b32_e32 v41, 0
	s_waitcnt lgkmcnt(0)
	v_mov_b32_e32 v35, v34
	s_mov_b32 s25, 2
	s_mov_b32 s26, 1
	s_mov_b32 s56, s24
	v_mov_b32_e32 v43, 0
	ds_read2_b32 v[250:251], v42 offset1:1

; DI void nsa_unit(const Params& P, int l, LAS char* lds, int b, int qt, int tid, int wave, int lane) {
;     ...
;             for (int e = 0; e < 8; ++e) {
;                 const int J = 8 * s8 + e;
;                 if (J >= 1 && J <= qt - 2) {
;                     const float v = impS[q * 65 + J]; int cnt = 0;
;                     for (int J2 = 1; J2 <= qt - 2; ++J2) { const float v2 = impS[q * 65 + J2]; cnt += (v2 > v || (v2 == v && J2 < J)) ? 1 : 0; }
;                     if (cnt < 13) bits |= 1u << e;
.LBB0_557:
	s_or_b64 exec, exec, s[34:35]
	v_or_b32_e32 v32, 5, v162
	v_cmp_ge_u32_e32 vcc, s11, v32
	s_and_saveexec_b64 s[34:35], vcc
	s_cbranch_execz .LBB0_564
	ds_read_b32 v34, v38 offset:20
	s_and_b32 s24, s11, -2
	v_mov_b32_e32 v33, v32
	v_add3_u32 v42, 0, 4, v37
	v_mov_b32_e32 v41, 0
	s_waitcnt lgkmcnt(0)
	v_mov_b32_e32 v35, v34
	s_mov_b32 s25, 2
	s_mov_b32 s26, 1
	s_mov_b32 s56, s24
	v_mov_b32_e32 v43, 0
	ds_read2_b32 v[250:251], v42 offset1:1

; DI void nsa_unit(const Params& P, int l, LAS char* lds, int b, int qt, int tid, int wave, int lane) {
;     ...
;             for (int e = 0; e < 8; ++e) {
;                 const int J = 8 * s8 + e;
;                 if (J >= 1 && J <= qt - 2) {
;                     const float v = impS[q * 65 + J]; int cnt = 0;
;                     for (int J2 = 1; J2 <= qt - 2; ++J2) { const float v2 = impS[q * 65 + J2]; cnt += (v2 > v || (v2 == v && J2 < J)) ? 1 : 0; }
;                     if (cnt < 13) bits |= 1u << e;
.LBB0_564:
	s_or_b64 exec, exec, s[34:35]
	v_or_b32_e32 v32, 6, v162
	v_cmp_ge_u32_e32 vcc, s11, v32
	s_and_saveexec_b64 s[34:35], vcc
	s_cbranch_execz .LBB0_571
	ds_read_b32 v34, v38 offset:24
	s_and_b32 s24, s11, -2
	v_mov_b32_e32 v33, v32
	v_add3_u32 v42, 0, 4, v37
	v_mov_b32_e32 v41, 0
	s_waitcnt lgkmcnt(0)
	v_mov_b32_e32 v35, v34
	s_mov_b32 s25, 2
	s_mov_b32 s26, 1
	s_mov_b32 s56, s24
	v_mov_b32_e32 v43, 0
	ds_read2_b32 v[250:251], v42 offset1:1

; DI void nsa_unit(const Params& P, int l, LAS char* lds, int b, int qt, int tid, int wave, int lane) {
;     ...
;             for (int e = 0; e < 8; ++e) {
;                 const int J = 8 * s8 + e;
;                 if (J >= 1 && J <= qt - 2) {
;                     const float v = impS[q * 65 + J]; int cnt = 0;
;                     for (int J2 = 1; J2 <= qt - 2; ++J2) { const float v2 = impS[q * 65 + J2]; cnt += (v2 > v || (v2 == v && J2 < J)) ? 1 : 0; }
;                     if (cnt < 13) bits |= 1u << e;
.LBB0_571:
	s_or_b64 exec, exec, s[34:35]
	v_or_b32_e32 v32, 7, v162
	v_cmp_ge_u32_e32 vcc, s11, v32
	s_and_saveexec_b64 s[34:35], vcc
	s_cbranch_execz .LBB0_578
	ds_read_b32 v34, v38 offset:28
	s_and_b32 s24, s11, -2
	v_mov_b32_e32 v33, v32
	v_mov_b32_e32 v38, 0
	s_mov_b32 s25, 2
	s_waitcnt lgkmcnt(0)
	v_mov_b32_e32 v35, v34
	s_mov_b32 s26, 1
	s_mov_b32 s56, s24
	v_mov_b32_e32 v41, 0
	ds_read2_b32 v[250:251], v40 offset1:1
.LBB0_573:
	s_waitcnt lgkmcnt(0)
	v_mov_b32_e32 v42, v250
	v_mov_b32_e32 v43, v251
	ds_read2_b32 v[250:251], v40 offset0:2 offset1:3
	v_cmp_lt_u32_e32 vcc, s26, v32
	v_cmp_lt_u32_e64 s[38:39], s25, v33
	s_add_i32 s26, s26, 2
	s_add_i32 s25, s25, 2
	v_cmp_eq_f32_e64 s[44:45], v42, v34
	v_cmp_eq_f32_e64 s[48:49], v43, v35
	v_cmp_gt_f32_e64 s[40:41], v43, v35
	v_cmp_gt_f32_e64 s[42:43], v42, v34
	s_and_b64 s[38:39], s[48:49], s[38:39]
	s_and_b64 s[44:45], s[44:45], vcc
	s_add_i32 s56, s56, -2
	s_or_b64 vcc, s[42:43], s[44:45]
	s_or_b64 s[38:39], s[40:41], s[38:39]
	v_add_u32_e32 v40, 8, v40
	v_addc_co_u32_e64 v41, s[38:39], 0, v41, s[38:39]
	s_cmp_lg_u32 s56, 0
	v_addc_co_u32_e32 v38, vcc, 0, v38, vcc
	s_cbranch_scc1 .LBB0_573
	s_cmp_eq_u32 s11, s24
	v_add_u32_e32 v33, v38, v41
	s_cbranch_scc1 .LBB0_577
	s_or_b32 s11, s11, 1
	s_lshl_b32 s24, s11, 2
	s_add_i32 s24, s24, 0
	v_add_u32_e32 v35, s24, v37
